# bundle27 with the waves 4-7 priority raise kept through the memory cross-attention section as well (reset moved to the end of P6)
# baseline (speedup 1.0000x reference)
.LBB0_1253:
	s_setprio 0
	s_cmp_gt_i32 s25, 7
	s_cbranch_scc0 .LBB0_1307
	s_waitcnt vmcnt(0)
	s_barrier
	s_mov_b64 s[0:1], exec
	v_readlane_b32 s2, v255, 2
	v_readlane_b32 s3, v255, 3
	s_and_b64 s[2:3], s[0:1], s[2:3]
	s_mov_b64 exec, s[2:3]
	s_cbranch_execz .LBB0_1306
	s_add_i32 s2, 0, 0x23fc0
	v_mov_b32_e32 v1, s2
	s_waitcnt vmcnt(0) expcnt(0) lgkmcnt(0)
	ds_read_b32 v4, v1
	s_add_i32 s2, 0, 0x23fc4
	v_mov_b32_e32 v1, s2
	ds_read_b32 v2, v1
	s_waitcnt lgkmcnt(1)
	v_cmp_ne_u32_e32 vcc, 0, v4
	s_cbranch_vccnz .LBB0_1270
	s_load_dwordx2 s[6:7], s[96:97], 0x4
	s_add_u32 s2, s26, 0x80200
	s_addc_u32 s3, s27, 0
	s_add_u32 s4, s26, 0x80400
	s_addc_u32 s5, s27, 0
	s_waitcnt lgkmcnt(0)
	s_mul_i32 s18, s6, s33
	s_add_u32 s6, s26, 0x80500
	s_mul_i32 s18, s18, s7
	s_addc_u32 s7, s27, 0
	s_add_u32 s8, s26, 0x80600
	s_addc_u32 s9, s27, 0
	s_add_u32 s10, s26, 0x80700
	s_addc_u32 s11, s27, 0
	s_add_u32 s12, s26, 0x80800
	s_addc_u32 s13, s27, 0
	s_add_u32 s14, s26, 0x80900
	s_addc_u32 s15, s27, 0
	s_add_u32 s16, s26, 0x80a00
	s_addc_u32 s17, s27, 0
	s_add_u32 s30, s26, 0x80b00
	s_addc_u32 s31, s27, 0
	s_add_u32 s34, s26, 0x80c00
	s_addc_u32 s35, s27, 0
	s_add_u32 s36, s26, 0x80d00
	s_addc_u32 s37, s27, 0
	s_add_u32 s38, s26, 0x80e00
	s_addc_u32 s39, s27, 0
	s_add_u32 s40, s26, 0x80f00
	s_addc_u32 s41, s27, 0
	s_add_u32 s42, s26, 0x81000
	s_addc_u32 s43, s27, 0
	s_add_u32 s44, s26, 0x81100
	s_addc_u32 s45, s27, 0
	s_add_u32 s46, s26, 0x81200
	s_addc_u32 s47, s27, 0
	s_add_u32 s48, s26, 0x81300
	s_addc_u32 s49, s27, 0
	s_mov_b32 s19, 1
	v_mov_b32_e32 v18, 0
	s_branch .LBB0_1258
